# epi7nop + phase-6 gate/mix epilogue: all 16 y_attn/y_four loads issued up front with counted vmcnt instead of one row group per round trip
# baseline (speedup 1.0000x reference)
; __device__ __forceinline__ unsigned cvt_pk_bf16(float lo, float hi) { unsigned r; asm volatile("v_cvt_pk_bf16_f32 %0, %1, %2" : "=v"(r) : "v"(lo), "v"(hi)); return r; }
;     __device__ __forceinline__ void operator()(const f32x4 (&acc)[2][2][4][2], const Unit& u, int wr, int wc, int fr, int fq) const {
;         const size_t tb = ((size_t)u.pm * BM * 4096 + (size_t)u.pn * HALF) * 2;
;         const char* yab = (const char*)ya + tb; const char* yfb = (const char*)yf + tb; char* mxb = (char*)mixed + tb;
;         const unsigned loff = ((unsigned)(wr * 64 + fr) * 4096u + (unsigned)(wc * 32 + 8 * fq)) * 2u;
;         const float* bgp = bgate + u.pn * HALF; const unsigned boff = (unsigned)(wc * 32 + 8 * fq) * 4u;
;         const f32x4 ba0 = *(const f32x4*)((const char*)bgp + boff), ba1 = *(const f32x4*)((const char*)bgp + boff + 16), bf0 = *(const f32x4*)((const char*)bgp + 16384 + boff), bf1 = *(const f32x4*)((const char*)bgp + 16384 + boff + 16);
; #pragma unroll
;         for (int ai = 0; ai < 2; ++ai)
; #pragma unroll
;             for (int m = 0; m < 4; ++m) { const size_t ro = (size_t)(ai * HALF + m * 16) * 4096 * 2;
;                 const v4u a = *(const v4u*)(yab + ro + loff), f = *(const v4u*)(yfb + ro + loff);
;                 const f32x4 ga0 = acc[ai][0][m][0] + ba0, ga1 = acc[ai][0][m][1] + ba1, gf0 = acc[ai][1][m][0] + bf0, gf1 = acc[ai][1][m][1] + bf1;
;                 float r[8];
;                 r[0] = fast_sigmoid(ga0[0]) * bflo(a.x) + fast_sigmoid(gf0[0]) * bflo(f.x); r[1] = fast_sigmoid(ga0[1]) * bfhi(a.x) + fast_sigmoid(gf0[1]) * bfhi(f.x);
;                 r[2] = fast_sigmoid(ga0[2]) * bflo(a.y) + fast_sigmoid(gf0[2]) * bflo(f.y); r[3] = fast_sigmoid(ga0[3]) * bfhi(a.y) + fast_sigmoid(gf0[3]) * bfhi(f.y);
;                 r[4] = fast_sigmoid(ga1[0]) * bflo(a.z) + fast_sigmoid(gf1[0]) * bflo(f.z); r[5] = fast_sigmoid(ga1[1]) * bfhi(a.z) + fast_sigmoid(gf1[1]) * bfhi(f.z);
;                 r[6] = fast_sigmoid(ga1[2]) * bflo(a.w) + fast_sigmoid(gf1[2]) * bflo(f.w); r[7] = fast_sigmoid(ga1[3]) * bfhi(a.w) + fast_sigmoid(gf1[3]) * bfhi(f.w);
;                 v4u w; w.x = cvt_pk_bf16(r[0], r[1]); w.y = cvt_pk_bf16(r[2], r[3]); w.z = cvt_pk_bf16(r[4], r[5]); w.w = cvt_pk_bf16(r[6], r[7]);
;                 *(v4u*)(mxb + ro + loff) = w; }
.LBB0_736:
	s_ashr_i32 s25, s24, 31
	s_ashr_i32 s27, s26, 31
	s_lshl_b64 s[18:19], s[26:27], 8
	s_lshl_b64 s[24:25], s[24:25], 21
	s_add_u32 s24, s24, s18
	s_addc_u32 s25, s25, s19
	s_lshl_b32 s18, s26, 7
	s_ashr_i32 s19, s18, 31
	s_lshl_b64 s[18:19], s[18:19], 2
	s_add_u32 s18, s6, s18
	s_addc_u32 s19, s7, s19
	v_lshl_add_u64 v[68:69], s[18:19], 0, v[144:145]
	v_add_co_u32_e32 v70, vcc, s58, v68
	v_lshl_add_u64 v[156:157], v[148:149], 0, s[24:25]
	s_nop 0
	v_addc_co_u32_e32 v71, vcc, 0, v69, vcc
	v_lshl_add_u64 v[158:159], v[146:147], 0, s[24:25]
	global_load_dwordx4 v[170:173], v[156:157], off
	global_load_dwordx4 v[174:177], v[158:159], off
	global_load_dwordx4 v[72:75], v[68:69], off offset:16
	global_load_dwordx4 v[84:87], v[68:69], off
	global_load_dwordx4 v[76:79], v[70:71], off
	v_lshl_add_u64 v[68:69], v[68:69], 0, s[12:13]
	global_load_dwordx4 v[68:71], v[68:69], off offset:16
	s_mov_b32 s99, 0
	s_mov_b32 s98, 0x20000
	v_lshl_add_u64 v[234:235], v[156:157], 0, s[98:99]
	v_lshl_add_u64 v[236:237], v[158:159], 0, s[98:99]
	global_load_dwordx4 v[178:181], v[234:235], off
	global_load_dwordx4 v[182:185], v[236:237], off
	s_mov_b32 s98, 0x40000
	v_lshl_add_u64 v[234:235], v[156:157], 0, s[98:99]
	v_lshl_add_u64 v[236:237], v[158:159], 0, s[98:99]
	global_load_dwordx4 v[186:189], v[234:235], off
	global_load_dwordx4 v[190:193], v[236:237], off
	s_mov_b32 s98, 0x60000
	v_lshl_add_u64 v[234:235], v[156:157], 0, s[98:99]
	v_lshl_add_u64 v[236:237], v[158:159], 0, s[98:99]
	global_load_dwordx4 v[194:197], v[234:235], off
	global_load_dwordx4 v[198:201], v[236:237], off
	s_mov_b32 s98, 0x100000
	v_lshl_add_u64 v[234:235], v[156:157], 0, s[98:99]
	v_lshl_add_u64 v[236:237], v[158:159], 0, s[98:99]
	global_load_dwordx4 v[202:205], v[234:235], off
	global_load_dwordx4 v[206:209], v[236:237], off
	s_mov_b32 s98, 0x120000
	v_lshl_add_u64 v[234:235], v[156:157], 0, s[98:99]
	v_lshl_add_u64 v[236:237], v[158:159], 0, s[98:99]
	global_load_dwordx4 v[210:213], v[234:235], off
	global_load_dwordx4 v[214:217], v[236:237], off
	s_mov_b32 s98, 0x140000
	v_lshl_add_u64 v[234:235], v[156:157], 0, s[98:99]
	v_lshl_add_u64 v[236:237], v[158:159], 0, s[98:99]
	global_load_dwordx4 v[218:221], v[234:235], off
	global_load_dwordx4 v[222:225], v[236:237], off
	s_mov_b32 s98, 0x160000
	v_lshl_add_u64 v[234:235], v[156:157], 0, s[98:99]
	v_lshl_add_u64 v[236:237], v[158:159], 0, s[98:99]
	global_load_dwordx4 v[226:229], v[234:235], off
	global_load_dwordx4 v[230:233], v[236:237], off
	v_lshl_add_u64 v[158:159], v[150:151], 0, s[24:25]
	s_waitcnt vmcnt(14)
	v_pk_add_f32 v[140:141], v[140:141], v[84:85]
	v_pk_add_f32 v[142:143], v[142:143], v[86:87]
	v_pk_add_f32 v[136:137], v[136:137], v[72:73]
	v_pk_add_f32 v[138:139], v[138:139], v[74:75]
	v_pk_add_f32 v[132:133], v[132:133], v[76:77]
	v_pk_add_f32 v[134:135], v[134:135], v[78:79]
	v_pk_add_f32 v[128:129], v[128:129], v[68:69]
	v_pk_add_f32 v[130:131], v[130:131], v[70:71]
	v_mul_f32_e32 v140, 0xbfb8aa3b, v140
	v_mul_f32_e32 v141, 0xbfb8aa3b, v141
	v_mul_f32_e32 v142, 0xbfb8aa3b, v142
	v_mul_f32_e32 v143, 0xbfb8aa3b, v143
	v_mul_f32_e32 v136, 0xbfb8aa3b, v136
	v_mul_f32_e32 v137, 0xbfb8aa3b, v137
	v_mul_f32_e32 v138, 0xbfb8aa3b, v138
	v_mul_f32_e32 v139, 0xbfb8aa3b, v139
	v_mul_f32_e32 v132, 0xbfb8aa3b, v132
	v_mul_f32_e32 v133, 0xbfb8aa3b, v133
	v_mul_f32_e32 v134, 0xbfb8aa3b, v134
	v_mul_f32_e32 v135, 0xbfb8aa3b, v135
	v_mul_f32_e32 v128, 0xbfb8aa3b, v128
	v_mul_f32_e32 v129, 0xbfb8aa3b, v129
	v_mul_f32_e32 v130, 0xbfb8aa3b, v130
	v_mul_f32_e32 v131, 0xbfb8aa3b, v131
	v_exp_f32_e32 v140, v140
	v_exp_f32_e32 v141, v141
	v_exp_f32_e32 v142, v142
	v_exp_f32_e32 v143, v143
	v_exp_f32_e32 v136, v136
	v_exp_f32_e32 v137, v137
	v_exp_f32_e32 v138, v138
	v_exp_f32_e32 v139, v139
	v_exp_f32_e32 v132, v132
	v_exp_f32_e32 v133, v133
	v_exp_f32_e32 v134, v134
	v_exp_f32_e32 v135, v135
	v_exp_f32_e32 v128, v128
	v_exp_f32_e32 v129, v129
	v_exp_f32_e32 v130, v130
	v_exp_f32_e32 v131, v131
	v_add_f32_e32 v140, 1.0, v140
	v_add_f32_e32 v141, 1.0, v141
	v_add_f32_e32 v142, 1.0, v142
	v_add_f32_e32 v143, 1.0, v143
	v_add_f32_e32 v136, 1.0, v136
	v_add_f32_e32 v137, 1.0, v137
	v_add_f32_e32 v138, 1.0, v138
	v_add_f32_e32 v139, 1.0, v139
	v_add_f32_e32 v132, 1.0, v132
	v_add_f32_e32 v133, 1.0, v133
	v_add_f32_e32 v134, 1.0, v134
	v_add_f32_e32 v135, 1.0, v135
	v_add_f32_e32 v128, 1.0, v128
	v_add_f32_e32 v129, 1.0, v129
	v_add_f32_e32 v130, 1.0, v130
	v_add_f32_e32 v131, 1.0, v131
	v_rcp_f32_e32 v140, v140
	v_rcp_f32_e32 v141, v141
	v_rcp_f32_e32 v142, v142
	v_rcp_f32_e32 v143, v143
	v_rcp_f32_e32 v136, v136
	v_rcp_f32_e32 v137, v137
	v_rcp_f32_e32 v138, v138
	v_rcp_f32_e32 v139, v139
	v_rcp_f32_e32 v132, v132
	v_rcp_f32_e32 v133, v133
	v_rcp_f32_e32 v134, v134
	v_rcp_f32_e32 v135, v135
	v_rcp_f32_e32 v128, v128
	v_rcp_f32_e32 v129, v129
	v_rcp_f32_e32 v130, v130
	v_rcp_f32_e32 v131, v131
	v_lshlrev_b32_e32 v238, 16, v174
	v_and_b32_e32 v239, 0xffff0000, v174
	v_lshlrev_b32_e32 v240, 16, v175
	v_and_b32_e32 v241, 0xffff0000, v175
	v_lshlrev_b32_e32 v242, 16, v176
	v_and_b32_e32 v243, 0xffff0000, v176
	v_lshlrev_b32_e32 v244, 16, v177
	v_and_b32_e32 v245, 0xffff0000, v177
	v_lshlrev_b32_e32 v246, 16, v170
	v_and_b32_e32 v247, 0xffff0000, v170
	v_lshlrev_b32_e32 v248, 16, v171
	v_and_b32_e32 v249, 0xffff0000, v171
	v_lshlrev_b32_e32 v250, 16, v172
	v_and_b32_e32 v251, 0xffff0000, v172
	v_lshlrev_b32_e32 v252, 16, v173
	v_and_b32_e32 v253, 0xffff0000, v173
	v_mul_f32_e32 v238, v140, v238
	v_mul_f32_e32 v239, v141, v239
	v_mul_f32_e32 v240, v142, v240
	v_mul_f32_e32 v241, v143, v241
	v_mul_f32_e32 v242, v136, v242
	v_mul_f32_e32 v243, v137, v243
	v_mul_f32_e32 v244, v138, v244
	v_mul_f32_e32 v245, v139, v245
	v_mul_f32_e32 v246, v132, v246
	v_mul_f32_e32 v247, v133, v247
	v_mul_f32_e32 v248, v134, v248
	v_mul_f32_e32 v249, v135, v249
	v_mul_f32_e32 v250, v128, v250
	v_mul_f32_e32 v251, v129, v251
	v_mul_f32_e32 v252, v130, v252
	v_mul_f32_e32 v253, v131, v253
	v_add_f32_e32 v238, v238, v246
	v_add_f32_e32 v239, v239, v247
	v_add_f32_e32 v240, v240, v248
	v_add_f32_e32 v241, v241, v249
	v_add_f32_e32 v242, v242, v250
	v_add_f32_e32 v243, v243, v251
	v_add_f32_e32 v244, v244, v252
	v_add_f32_e32 v245, v245, v253
	v_cvt_pk_bf16_f32 v140, v238, v239
	v_cvt_pk_bf16_f32 v141, v240, v241
	v_cvt_pk_bf16_f32 v142, v242, v243
	v_cvt_pk_bf16_f32 v143, v244, v245
	global_store_dwordx4 v[158:159], v[140:143], off
	s_waitcnt vmcnt(13)
; __device__ __forceinline__ unsigned cvt_pk_bf16(float lo, float hi) { unsigned r; asm volatile("v_cvt_pk_bf16_f32 %0, %1, %2" : "=v"(r) : "v"(lo), "v"(hi)); return r; }
; __device__ __forceinline__ float fast_sigmoid(float x) { return __builtin_amdgcn_rcpf(1.0f + __builtin_amdgcn_exp2f(-1.4426950408889634f * x)); }
;     __device__ __forceinline__ void operator()(const f32x4 (&acc)[2][2][4][2], const Unit& u, int wr, int wc, int fr, int fq) const {
;     ...
;             for (int m = 0; m < 4; ++m) { const size_t ro = (size_t)(ai * HALF + m * 16) * 4096 * 2;
;                 const v4u a = *(const v4u*)(yab + ro + loff), f = *(const v4u*)(yfb + ro + loff);
;                 const f32x4 ga0 = acc[ai][0][m][0] + ba0, ga1 = acc[ai][0][m][1] + ba1, gf0 = acc[ai][1][m][0] + bf0, gf1 = acc[ai][1][m][1] + bf1;
;                 float r[8];
;                 r[0] = fast_sigmoid(ga0[0]) * bflo(a.x) + fast_sigmoid(gf0[0]) * bflo(f.x); r[1] = fast_sigmoid(ga0[1]) * bfhi(a.x) + fast_sigmoid(gf0[1]) * bfhi(f.x);
;                 r[2] = fast_sigmoid(ga0[2]) * bflo(a.y) + fast_sigmoid(gf0[2]) * bflo(f.y); r[3] = fast_sigmoid(ga0[3]) * bfhi(a.y) + fast_sigmoid(gf0[3]) * bfhi(f.y);
;                 r[4] = fast_sigmoid(ga1[0]) * bflo(a.z) + fast_sigmoid(gf1[0]) * bflo(f.z); r[5] = fast_sigmoid(ga1[1]) * bfhi(a.z) + fast_sigmoid(gf1[1]) * bfhi(f.z);
;                 r[6] = fast_sigmoid(ga1[2]) * bflo(a.w) + fast_sigmoid(gf1[2]) * bflo(f.w); r[7] = fast_sigmoid(ga1[3]) * bfhi(a.w) + fast_sigmoid(gf1[3]) * bfhi(f.w);
;                 v4u w; w.x = cvt_pk_bf16(r[0], r[1]); w.y = cvt_pk_bf16(r[2], r[3]); w.z = cvt_pk_bf16(r[4], r[5]); w.w = cvt_pk_bf16(r[6], r[7]);
;                 *(v4u*)(mxb + ro + loff) = w; }
	v_pk_add_f32 v[124:125], v[124:125], v[84:85]
	v_pk_add_f32 v[126:127], v[126:127], v[86:87]
	v_pk_add_f32 v[120:121], v[120:121], v[72:73]
	v_pk_add_f32 v[122:123], v[122:123], v[74:75]
	v_pk_add_f32 v[116:117], v[116:117], v[76:77]
	v_pk_add_f32 v[118:119], v[118:119], v[78:79]
	v_pk_add_f32 v[112:113], v[112:113], v[68:69]
	v_pk_add_f32 v[114:115], v[114:115], v[70:71]
	v_mul_f32_e32 v124, 0xbfb8aa3b, v124
	v_mul_f32_e32 v125, 0xbfb8aa3b, v125
	v_mul_f32_e32 v126, 0xbfb8aa3b, v126
	v_mul_f32_e32 v127, 0xbfb8aa3b, v127
	v_mul_f32_e32 v120, 0xbfb8aa3b, v120
	v_mul_f32_e32 v121, 0xbfb8aa3b, v121
	v_mul_f32_e32 v122, 0xbfb8aa3b, v122
	v_mul_f32_e32 v123, 0xbfb8aa3b, v123
	v_mul_f32_e32 v116, 0xbfb8aa3b, v116
	v_mul_f32_e32 v117, 0xbfb8aa3b, v117
	v_mul_f32_e32 v118, 0xbfb8aa3b, v118
	v_mul_f32_e32 v119, 0xbfb8aa3b, v119
	v_mul_f32_e32 v112, 0xbfb8aa3b, v112
	v_mul_f32_e32 v113, 0xbfb8aa3b, v113
	v_mul_f32_e32 v114, 0xbfb8aa3b, v114
	v_mul_f32_e32 v115, 0xbfb8aa3b, v115
	v_exp_f32_e32 v124, v124
	v_exp_f32_e32 v125, v125
	v_exp_f32_e32 v126, v126
	v_exp_f32_e32 v127, v127
	v_exp_f32_e32 v120, v120
	v_exp_f32_e32 v121, v121
	v_exp_f32_e32 v122, v122
	v_exp_f32_e32 v123, v123
	v_exp_f32_e32 v116, v116
	v_exp_f32_e32 v117, v117
	v_exp_f32_e32 v118, v118
	v_exp_f32_e32 v119, v119
	v_exp_f32_e32 v112, v112
	v_exp_f32_e32 v113, v113
	v_exp_f32_e32 v114, v114
	v_exp_f32_e32 v115, v115
	v_add_f32_e32 v124, 1.0, v124
	v_add_f32_e32 v125, 1.0, v125
	v_add_f32_e32 v126, 1.0, v126
	v_add_f32_e32 v127, 1.0, v127
	v_add_f32_e32 v120, 1.0, v120
	v_add_f32_e32 v121, 1.0, v121
	v_add_f32_e32 v122, 1.0, v122
	v_add_f32_e32 v123, 1.0, v123
	v_add_f32_e32 v116, 1.0, v116
	v_add_f32_e32 v117, 1.0, v117
	v_add_f32_e32 v118, 1.0, v118
	v_add_f32_e32 v119, 1.0, v119
	v_add_f32_e32 v112, 1.0, v112
	v_add_f32_e32 v113, 1.0, v113
	v_add_f32_e32 v114, 1.0, v114
	v_add_f32_e32 v115, 1.0, v115
	v_rcp_f32_e32 v124, v124
	v_rcp_f32_e32 v125, v125
	v_rcp_f32_e32 v126, v126
	v_rcp_f32_e32 v127, v127
	v_rcp_f32_e32 v120, v120
	v_rcp_f32_e32 v121, v121
	v_rcp_f32_e32 v122, v122
	v_rcp_f32_e32 v123, v123
	v_rcp_f32_e32 v116, v116
	v_rcp_f32_e32 v117, v117
	v_rcp_f32_e32 v118, v118
	v_rcp_f32_e32 v119, v119
	v_rcp_f32_e32 v112, v112
	v_rcp_f32_e32 v113, v113
	v_rcp_f32_e32 v114, v114
	v_rcp_f32_e32 v115, v115
	v_lshlrev_b32_e32 v238, 16, v182
	v_and_b32_e32 v239, 0xffff0000, v182
	v_lshlrev_b32_e32 v240, 16, v183
	v_and_b32_e32 v241, 0xffff0000, v183
	v_lshlrev_b32_e32 v242, 16, v184
	v_and_b32_e32 v243, 0xffff0000, v184
	v_lshlrev_b32_e32 v244, 16, v185
	v_and_b32_e32 v245, 0xffff0000, v185
	v_lshlrev_b32_e32 v246, 16, v178
	v_and_b32_e32 v247, 0xffff0000, v178
	v_lshlrev_b32_e32 v248, 16, v179
	v_and_b32_e32 v249, 0xffff0000, v179
	v_lshlrev_b32_e32 v250, 16, v180
	v_and_b32_e32 v251, 0xffff0000, v180
	v_lshlrev_b32_e32 v252, 16, v181
	v_and_b32_e32 v253, 0xffff0000, v181
	v_mul_f32_e32 v238, v124, v238
	v_mul_f32_e32 v239, v125, v239
	v_mul_f32_e32 v240, v126, v240
	v_mul_f32_e32 v241, v127, v241
	v_mul_f32_e32 v242, v120, v242
	v_mul_f32_e32 v243, v121, v243
	v_mul_f32_e32 v244, v122, v244
	v_mul_f32_e32 v245, v123, v245
	v_mul_f32_e32 v246, v116, v246
	v_mul_f32_e32 v247, v117, v247
	v_mul_f32_e32 v248, v118, v248
	v_mul_f32_e32 v249, v119, v249
	v_mul_f32_e32 v250, v112, v250
	v_mul_f32_e32 v251, v113, v251
	v_mul_f32_e32 v252, v114, v252
	v_mul_f32_e32 v253, v115, v253
	v_add_f32_e32 v238, v238, v246
	v_add_f32_e32 v239, v239, v247
	v_add_f32_e32 v240, v240, v248
	v_add_f32_e32 v241, v241, v249
	v_add_f32_e32 v242, v242, v250
	v_add_f32_e32 v243, v243, v251
	v_add_f32_e32 v244, v244, v252
	v_add_f32_e32 v245, v245, v253
	v_cvt_pk_bf16_f32 v124, v238, v239
	v_cvt_pk_bf16_f32 v125, v240, v241
	v_cvt_pk_bf16_f32 v126, v242, v243
	v_cvt_pk_bf16_f32 v127, v244, v245
	s_mov_b32 s98, 0x20000
	v_lshl_add_u64 v[234:235], v[158:159], 0, s[98:99]
	global_store_dwordx4 v[234:235], v[124:127], off
	s_waitcnt vmcnt(12)
	v_pk_add_f32 v[108:109], v[108:109], v[84:85]
	v_pk_add_f32 v[110:111], v[110:111], v[86:87]
	v_pk_add_f32 v[104:105], v[104:105], v[72:73]
	v_pk_add_f32 v[106:107], v[106:107], v[74:75]
	v_pk_add_f32 v[100:101], v[100:101], v[76:77]
	v_pk_add_f32 v[102:103], v[102:103], v[78:79]
	v_pk_add_f32 v[96:97], v[96:97], v[68:69]
	v_pk_add_f32 v[98:99], v[98:99], v[70:71]
	v_mul_f32_e32 v108, 0xbfb8aa3b, v108
	v_mul_f32_e32 v109, 0xbfb8aa3b, v109
	v_mul_f32_e32 v110, 0xbfb8aa3b, v110
	v_mul_f32_e32 v111, 0xbfb8aa3b, v111
	v_mul_f32_e32 v104, 0xbfb8aa3b, v104
	v_mul_f32_e32 v105, 0xbfb8aa3b, v105
	v_mul_f32_e32 v106, 0xbfb8aa3b, v106
	v_mul_f32_e32 v107, 0xbfb8aa3b, v107
	v_mul_f32_e32 v100, 0xbfb8aa3b, v100
	v_mul_f32_e32 v101, 0xbfb8aa3b, v101
	v_mul_f32_e32 v102, 0xbfb8aa3b, v102
	v_mul_f32_e32 v103, 0xbfb8aa3b, v103
	v_mul_f32_e32 v96, 0xbfb8aa3b, v96
	v_mul_f32_e32 v97, 0xbfb8aa3b, v97
	v_mul_f32_e32 v98, 0xbfb8aa3b, v98
	v_mul_f32_e32 v99, 0xbfb8aa3b, v99
	v_exp_f32_e32 v108, v108
	v_exp_f32_e32 v109, v109
	v_exp_f32_e32 v110, v110
	v_exp_f32_e32 v111, v111
	v_exp_f32_e32 v104, v104
	v_exp_f32_e32 v105, v105
	v_exp_f32_e32 v106, v106
	v_exp_f32_e32 v107, v107
	v_exp_f32_e32 v100, v100
	v_exp_f32_e32 v101, v101
	v_exp_f32_e32 v102, v102
	v_exp_f32_e32 v103, v103
	v_exp_f32_e32 v96, v96
	v_exp_f32_e32 v97, v97
	v_exp_f32_e32 v98, v98
	v_exp_f32_e32 v99, v99
	v_add_f32_e32 v108, 1.0, v108
	v_add_f32_e32 v109, 1.0, v109
	v_add_f32_e32 v110, 1.0, v110
	v_add_f32_e32 v111, 1.0, v111
	v_add_f32_e32 v104, 1.0, v104
	v_add_f32_e32 v105, 1.0, v105
	v_add_f32_e32 v106, 1.0, v106
	v_add_f32_e32 v107, 1.0, v107
	v_add_f32_e32 v100, 1.0, v100
	v_add_f32_e32 v101, 1.0, v101
; __device__ __forceinline__ unsigned cvt_pk_bf16(float lo, float hi) { unsigned r; asm volatile("v_cvt_pk_bf16_f32 %0, %1, %2" : "=v"(r) : "v"(lo), "v"(hi)); return r; }
; __device__ __forceinline__ float fast_sigmoid(float x) { return __builtin_amdgcn_rcpf(1.0f + __builtin_amdgcn_exp2f(-1.4426950408889634f * x)); }
;     __device__ __forceinline__ void operator()(const f32x4 (&acc)[2][2][4][2], const Unit& u, int wr, int wc, int fr, int fq) const {
;     ...
;             for (int m = 0; m < 4; ++m) { const size_t ro = (size_t)(ai * HALF + m * 16) * 4096 * 2;
;                 const v4u a = *(const v4u*)(yab + ro + loff), f = *(const v4u*)(yfb + ro + loff);
;                 const f32x4 ga0 = acc[ai][0][m][0] + ba0, ga1 = acc[ai][0][m][1] + ba1, gf0 = acc[ai][1][m][0] + bf0, gf1 = acc[ai][1][m][1] + bf1;
;                 float r[8];
;                 r[0] = fast_sigmoid(ga0[0]) * bflo(a.x) + fast_sigmoid(gf0[0]) * bflo(f.x); r[1] = fast_sigmoid(ga0[1]) * bfhi(a.x) + fast_sigmoid(gf0[1]) * bfhi(f.x);
;                 r[2] = fast_sigmoid(ga0[2]) * bflo(a.y) + fast_sigmoid(gf0[2]) * bflo(f.y); r[3] = fast_sigmoid(ga0[3]) * bfhi(a.y) + fast_sigmoid(gf0[3]) * bfhi(f.y);
;                 r[4] = fast_sigmoid(ga1[0]) * bflo(a.z) + fast_sigmoid(gf1[0]) * bflo(f.z); r[5] = fast_sigmoid(ga1[1]) * bfhi(a.z) + fast_sigmoid(gf1[1]) * bfhi(f.z);
;                 r[6] = fast_sigmoid(ga1[2]) * bflo(a.w) + fast_sigmoid(gf1[2]) * bflo(f.w); r[7] = fast_sigmoid(ga1[3]) * bfhi(a.w) + fast_sigmoid(gf1[3]) * bfhi(f.w);
;                 v4u w; w.x = cvt_pk_bf16(r[0], r[1]); w.y = cvt_pk_bf16(r[2], r[3]); w.z = cvt_pk_bf16(r[4], r[5]); w.w = cvt_pk_bf16(r[6], r[7]);
;                 *(v4u*)(mxb + ro + loff) = w; }
	v_add_f32_e32 v102, 1.0, v102
	v_add_f32_e32 v103, 1.0, v103
	v_add_f32_e32 v96, 1.0, v96
	v_add_f32_e32 v97, 1.0, v97
	v_add_f32_e32 v98, 1.0, v98
	v_add_f32_e32 v99, 1.0, v99
	v_rcp_f32_e32 v108, v108
	v_rcp_f32_e32 v109, v109
	v_rcp_f32_e32 v110, v110
	v_rcp_f32_e32 v111, v111
	v_rcp_f32_e32 v104, v104
	v_rcp_f32_e32 v105, v105
	v_rcp_f32_e32 v106, v106
	v_rcp_f32_e32 v107, v107
	v_rcp_f32_e32 v100, v100
	v_rcp_f32_e32 v101, v101
	v_rcp_f32_e32 v102, v102
	v_rcp_f32_e32 v103, v103
	v_rcp_f32_e32 v96, v96
	v_rcp_f32_e32 v97, v97
	v_rcp_f32_e32 v98, v98
	v_rcp_f32_e32 v99, v99
	v_lshlrev_b32_e32 v238, 16, v190
	v_and_b32_e32 v239, 0xffff0000, v190
	v_lshlrev_b32_e32 v240, 16, v191
	v_and_b32_e32 v241, 0xffff0000, v191
	v_lshlrev_b32_e32 v242, 16, v192
	v_and_b32_e32 v243, 0xffff0000, v192
	v_lshlrev_b32_e32 v244, 16, v193
	v_and_b32_e32 v245, 0xffff0000, v193
	v_lshlrev_b32_e32 v246, 16, v186
	v_and_b32_e32 v247, 0xffff0000, v186
	v_lshlrev_b32_e32 v248, 16, v187
	v_and_b32_e32 v249, 0xffff0000, v187
	v_lshlrev_b32_e32 v250, 16, v188
	v_and_b32_e32 v251, 0xffff0000, v188
	v_lshlrev_b32_e32 v252, 16, v189
	v_and_b32_e32 v253, 0xffff0000, v189
	v_mul_f32_e32 v238, v108, v238
	v_mul_f32_e32 v239, v109, v239
	v_mul_f32_e32 v240, v110, v240
	v_mul_f32_e32 v241, v111, v241
	v_mul_f32_e32 v242, v104, v242
	v_mul_f32_e32 v243, v105, v243
	v_mul_f32_e32 v244, v106, v244
	v_mul_f32_e32 v245, v107, v245
	v_mul_f32_e32 v246, v100, v246
	v_mul_f32_e32 v247, v101, v247
	v_mul_f32_e32 v248, v102, v248
	v_mul_f32_e32 v249, v103, v249
	v_mul_f32_e32 v250, v96, v250
	v_mul_f32_e32 v251, v97, v251
	v_mul_f32_e32 v252, v98, v252
	v_mul_f32_e32 v253, v99, v253
	v_add_f32_e32 v238, v238, v246
	v_add_f32_e32 v239, v239, v247
	v_add_f32_e32 v240, v240, v248
	v_add_f32_e32 v241, v241, v249
	v_add_f32_e32 v242, v242, v250
	v_add_f32_e32 v243, v243, v251
	v_add_f32_e32 v244, v244, v252
	v_add_f32_e32 v245, v245, v253
	v_cvt_pk_bf16_f32 v108, v238, v239
	v_cvt_pk_bf16_f32 v109, v240, v241
	v_cvt_pk_bf16_f32 v110, v242, v243
	v_cvt_pk_bf16_f32 v111, v244, v245
	s_mov_b32 s98, 0x40000
	v_lshl_add_u64 v[234:235], v[158:159], 0, s[98:99]
	global_store_dwordx4 v[234:235], v[108:111], off
	s_waitcnt vmcnt(11)
	v_pk_add_f32 v[92:93], v[92:93], v[84:85]
	v_pk_add_f32 v[94:95], v[94:95], v[86:87]
	v_pk_add_f32 v[88:89], v[88:89], v[72:73]
	v_pk_add_f32 v[90:91], v[90:91], v[74:75]
	v_pk_add_f32 v[80:81], v[80:81], v[76:77]
	v_pk_add_f32 v[82:83], v[82:83], v[78:79]
	v_pk_add_f32 v[64:65], v[64:65], v[68:69]
	v_pk_add_f32 v[66:67], v[66:67], v[70:71]
	v_mul_f32_e32 v92, 0xbfb8aa3b, v92
	v_mul_f32_e32 v93, 0xbfb8aa3b, v93
	v_mul_f32_e32 v94, 0xbfb8aa3b, v94
	v_mul_f32_e32 v95, 0xbfb8aa3b, v95
	v_mul_f32_e32 v88, 0xbfb8aa3b, v88
	v_mul_f32_e32 v89, 0xbfb8aa3b, v89
	v_mul_f32_e32 v90, 0xbfb8aa3b, v90
	v_mul_f32_e32 v91, 0xbfb8aa3b, v91
	v_mul_f32_e32 v80, 0xbfb8aa3b, v80
	v_mul_f32_e32 v81, 0xbfb8aa3b, v81
	v_mul_f32_e32 v82, 0xbfb8aa3b, v82
	v_mul_f32_e32 v83, 0xbfb8aa3b, v83
	v_mul_f32_e32 v64, 0xbfb8aa3b, v64
	v_mul_f32_e32 v65, 0xbfb8aa3b, v65
	v_mul_f32_e32 v66, 0xbfb8aa3b, v66
	v_mul_f32_e32 v67, 0xbfb8aa3b, v67
	v_exp_f32_e32 v92, v92
	v_exp_f32_e32 v93, v93
	v_exp_f32_e32 v94, v94
	v_exp_f32_e32 v95, v95
	v_exp_f32_e32 v88, v88
	v_exp_f32_e32 v89, v89
	v_exp_f32_e32 v90, v90
	v_exp_f32_e32 v91, v91
	v_exp_f32_e32 v80, v80
	v_exp_f32_e32 v81, v81
	v_exp_f32_e32 v82, v82
	v_exp_f32_e32 v83, v83
	v_exp_f32_e32 v64, v64
	v_exp_f32_e32 v65, v65
	v_exp_f32_e32 v66, v66
	v_exp_f32_e32 v67, v67
	v_add_f32_e32 v92, 1.0, v92
	v_add_f32_e32 v93, 1.0, v93
	v_add_f32_e32 v94, 1.0, v94
	v_add_f32_e32 v95, 1.0, v95
	v_add_f32_e32 v88, 1.0, v88
	v_add_f32_e32 v89, 1.0, v89
	v_add_f32_e32 v90, 1.0, v90
	v_add_f32_e32 v91, 1.0, v91
	v_add_f32_e32 v80, 1.0, v80
	v_add_f32_e32 v81, 1.0, v81
	v_add_f32_e32 v82, 1.0, v82
	v_add_f32_e32 v83, 1.0, v83
	v_add_f32_e32 v64, 1.0, v64
	v_add_f32_e32 v65, 1.0, v65
	v_add_f32_e32 v66, 1.0, v66
	v_add_f32_e32 v67, 1.0, v67
	v_rcp_f32_e32 v92, v92
	v_rcp_f32_e32 v93, v93
	v_rcp_f32_e32 v94, v94
	v_rcp_f32_e32 v95, v95
	v_rcp_f32_e32 v88, v88
	v_rcp_f32_e32 v89, v89
	v_rcp_f32_e32 v90, v90
	v_rcp_f32_e32 v91, v91
	v_rcp_f32_e32 v80, v80
	v_rcp_f32_e32 v81, v81
	v_rcp_f32_e32 v82, v82
	v_rcp_f32_e32 v83, v83
	v_rcp_f32_e32 v64, v64
	v_rcp_f32_e32 v65, v65
	v_rcp_f32_e32 v66, v66
	v_rcp_f32_e32 v67, v67
	v_lshlrev_b32_e32 v238, 16, v198
	v_and_b32_e32 v239, 0xffff0000, v198
	v_lshlrev_b32_e32 v240, 16, v199
	v_and_b32_e32 v241, 0xffff0000, v199
	v_lshlrev_b32_e32 v242, 16, v200
	v_and_b32_e32 v243, 0xffff0000, v200
	v_lshlrev_b32_e32 v244, 16, v201
	v_and_b32_e32 v245, 0xffff0000, v201
	v_lshlrev_b32_e32 v246, 16, v194
	v_and_b32_e32 v247, 0xffff0000, v194
	v_lshlrev_b32_e32 v248, 16, v195
	v_and_b32_e32 v249, 0xffff0000, v195
	v_lshlrev_b32_e32 v250, 16, v196
	v_and_b32_e32 v251, 0xffff0000, v196
	v_lshlrev_b32_e32 v252, 16, v197
	v_and_b32_e32 v253, 0xffff0000, v197
	v_mul_f32_e32 v238, v92, v238
	v_mul_f32_e32 v239, v93, v239
	v_mul_f32_e32 v240, v94, v240
	v_mul_f32_e32 v241, v95, v241
	v_mul_f32_e32 v242, v88, v242
	v_mul_f32_e32 v243, v89, v243
	v_mul_f32_e32 v244, v90, v244
	v_mul_f32_e32 v245, v91, v245
	v_mul_f32_e32 v246, v80, v246
	v_mul_f32_e32 v247, v81, v247
	v_mul_f32_e32 v248, v82, v248
	v_mul_f32_e32 v249, v83, v249
	v_mul_f32_e32 v250, v64, v250
	v_mul_f32_e32 v251, v65, v251
	v_mul_f32_e32 v252, v66, v252
	v_mul_f32_e32 v253, v67, v253
	v_add_f32_e32 v238, v238, v246
	v_add_f32_e32 v239, v239, v247
	v_add_f32_e32 v240, v240, v248
	v_add_f32_e32 v241, v241, v249
	v_add_f32_e32 v242, v242, v250
	v_add_f32_e32 v243, v243, v251
	v_add_f32_e32 v244, v244, v252
	v_add_f32_e32 v245, v245, v253
	v_cvt_pk_bf16_f32 v92, v238, v239
	v_cvt_pk_bf16_f32 v93, v240, v241
	v_cvt_pk_bf16_f32 v94, v242, v243
	v_cvt_pk_bf16_f32 v95, v244, v245
	s_mov_b32 s98, 0x60000
	v_lshl_add_u64 v[234:235], v[158:159], 0, s[98:99]
	global_store_dwordx4 v[234:235], v[92:95], off
	s_waitcnt vmcnt(10)
; __device__ __forceinline__ unsigned cvt_pk_bf16(float lo, float hi) { unsigned r; asm volatile("v_cvt_pk_bf16_f32 %0, %1, %2" : "=v"(r) : "v"(lo), "v"(hi)); return r; }
; __device__ __forceinline__ float fast_sigmoid(float x) { return __builtin_amdgcn_rcpf(1.0f + __builtin_amdgcn_exp2f(-1.4426950408889634f * x)); }
;     __device__ __forceinline__ void operator()(const f32x4 (&acc)[2][2][4][2], const Unit& u, int wr, int wc, int fr, int fq) const {
;     ...
;             for (int m = 0; m < 4; ++m) { const size_t ro = (size_t)(ai * HALF + m * 16) * 4096 * 2;
;                 const v4u a = *(const v4u*)(yab + ro + loff), f = *(const v4u*)(yfb + ro + loff);
;                 const f32x4 ga0 = acc[ai][0][m][0] + ba0, ga1 = acc[ai][0][m][1] + ba1, gf0 = acc[ai][1][m][0] + bf0, gf1 = acc[ai][1][m][1] + bf1;
;                 float r[8];
;                 r[0] = fast_sigmoid(ga0[0]) * bflo(a.x) + fast_sigmoid(gf0[0]) * bflo(f.x); r[1] = fast_sigmoid(ga0[1]) * bfhi(a.x) + fast_sigmoid(gf0[1]) * bfhi(f.x);
;                 r[2] = fast_sigmoid(ga0[2]) * bflo(a.y) + fast_sigmoid(gf0[2]) * bflo(f.y); r[3] = fast_sigmoid(ga0[3]) * bfhi(a.y) + fast_sigmoid(gf0[3]) * bfhi(f.y);
;                 r[4] = fast_sigmoid(ga1[0]) * bflo(a.z) + fast_sigmoid(gf1[0]) * bflo(f.z); r[5] = fast_sigmoid(ga1[1]) * bfhi(a.z) + fast_sigmoid(gf1[1]) * bfhi(f.z);
;                 r[6] = fast_sigmoid(ga1[2]) * bflo(a.w) + fast_sigmoid(gf1[2]) * bflo(f.w); r[7] = fast_sigmoid(ga1[3]) * bfhi(a.w) + fast_sigmoid(gf1[3]) * bfhi(f.w);
;                 v4u w; w.x = cvt_pk_bf16(r[0], r[1]); w.y = cvt_pk_bf16(r[2], r[3]); w.z = cvt_pk_bf16(r[4], r[5]); w.w = cvt_pk_bf16(r[6], r[7]);
;                 *(v4u*)(mxb + ro + loff) = w; }
	v_pk_add_f32 v[60:61], v[60:61], v[84:85]
	v_pk_add_f32 v[62:63], v[62:63], v[86:87]
	v_pk_add_f32 v[56:57], v[56:57], v[72:73]
	v_pk_add_f32 v[58:59], v[58:59], v[74:75]
	v_pk_add_f32 v[52:53], v[52:53], v[76:77]
	v_pk_add_f32 v[54:55], v[54:55], v[78:79]
	v_pk_add_f32 v[48:49], v[48:49], v[68:69]
	v_pk_add_f32 v[50:51], v[50:51], v[70:71]
	v_mul_f32_e32 v60, 0xbfb8aa3b, v60
	v_mul_f32_e32 v61, 0xbfb8aa3b, v61
	v_mul_f32_e32 v62, 0xbfb8aa3b, v62
	v_mul_f32_e32 v63, 0xbfb8aa3b, v63
	v_mul_f32_e32 v56, 0xbfb8aa3b, v56
	v_mul_f32_e32 v57, 0xbfb8aa3b, v57
	v_mul_f32_e32 v58, 0xbfb8aa3b, v58
	v_mul_f32_e32 v59, 0xbfb8aa3b, v59
	v_mul_f32_e32 v52, 0xbfb8aa3b, v52
	v_mul_f32_e32 v53, 0xbfb8aa3b, v53
	v_mul_f32_e32 v54, 0xbfb8aa3b, v54
	v_mul_f32_e32 v55, 0xbfb8aa3b, v55
	v_mul_f32_e32 v48, 0xbfb8aa3b, v48
	v_mul_f32_e32 v49, 0xbfb8aa3b, v49
	v_mul_f32_e32 v50, 0xbfb8aa3b, v50
	v_mul_f32_e32 v51, 0xbfb8aa3b, v51
	v_exp_f32_e32 v60, v60
	v_exp_f32_e32 v61, v61
	v_exp_f32_e32 v62, v62
	v_exp_f32_e32 v63, v63
	v_exp_f32_e32 v56, v56
	v_exp_f32_e32 v57, v57
	v_exp_f32_e32 v58, v58
	v_exp_f32_e32 v59, v59
	v_exp_f32_e32 v52, v52
	v_exp_f32_e32 v53, v53
	v_exp_f32_e32 v54, v54
	v_exp_f32_e32 v55, v55
	v_exp_f32_e32 v48, v48
	v_exp_f32_e32 v49, v49
	v_exp_f32_e32 v50, v50
	v_exp_f32_e32 v51, v51
	v_add_f32_e32 v60, 1.0, v60
	v_add_f32_e32 v61, 1.0, v61
	v_add_f32_e32 v62, 1.0, v62
	v_add_f32_e32 v63, 1.0, v63
	v_add_f32_e32 v56, 1.0, v56
	v_add_f32_e32 v57, 1.0, v57
	v_add_f32_e32 v58, 1.0, v58
	v_add_f32_e32 v59, 1.0, v59
	v_add_f32_e32 v52, 1.0, v52
	v_add_f32_e32 v53, 1.0, v53
	v_add_f32_e32 v54, 1.0, v54
	v_add_f32_e32 v55, 1.0, v55
	v_add_f32_e32 v48, 1.0, v48
	v_add_f32_e32 v49, 1.0, v49
	v_add_f32_e32 v50, 1.0, v50
	v_add_f32_e32 v51, 1.0, v51
	v_rcp_f32_e32 v60, v60
	v_rcp_f32_e32 v61, v61
	v_rcp_f32_e32 v62, v62
	v_rcp_f32_e32 v63, v63
	v_rcp_f32_e32 v56, v56
	v_rcp_f32_e32 v57, v57
	v_rcp_f32_e32 v58, v58
	v_rcp_f32_e32 v59, v59
	v_rcp_f32_e32 v52, v52
	v_rcp_f32_e32 v53, v53
	v_rcp_f32_e32 v54, v54
	v_rcp_f32_e32 v55, v55
	v_rcp_f32_e32 v48, v48
	v_rcp_f32_e32 v49, v49
	v_rcp_f32_e32 v50, v50
	v_rcp_f32_e32 v51, v51
	v_lshlrev_b32_e32 v238, 16, v206
	v_and_b32_e32 v239, 0xffff0000, v206
	v_lshlrev_b32_e32 v240, 16, v207
	v_and_b32_e32 v241, 0xffff0000, v207
	v_lshlrev_b32_e32 v242, 16, v208
	v_and_b32_e32 v243, 0xffff0000, v208
	v_lshlrev_b32_e32 v244, 16, v209
	v_and_b32_e32 v245, 0xffff0000, v209
	v_lshlrev_b32_e32 v246, 16, v202
	v_and_b32_e32 v247, 0xffff0000, v202
	v_lshlrev_b32_e32 v248, 16, v203
	v_and_b32_e32 v249, 0xffff0000, v203
	v_lshlrev_b32_e32 v250, 16, v204
	v_and_b32_e32 v251, 0xffff0000, v204
	v_lshlrev_b32_e32 v252, 16, v205
	v_and_b32_e32 v253, 0xffff0000, v205
	v_mul_f32_e32 v238, v60, v238
	v_mul_f32_e32 v239, v61, v239
	v_mul_f32_e32 v240, v62, v240
	v_mul_f32_e32 v241, v63, v241
	v_mul_f32_e32 v242, v56, v242
	v_mul_f32_e32 v243, v57, v243
	v_mul_f32_e32 v244, v58, v244
	v_mul_f32_e32 v245, v59, v245
	v_mul_f32_e32 v246, v52, v246
	v_mul_f32_e32 v247, v53, v247
	v_mul_f32_e32 v248, v54, v248
	v_mul_f32_e32 v249, v55, v249
	v_mul_f32_e32 v250, v48, v250
	v_mul_f32_e32 v251, v49, v251
	v_mul_f32_e32 v252, v50, v252
	v_mul_f32_e32 v253, v51, v253
	v_add_f32_e32 v238, v238, v246
	v_add_f32_e32 v239, v239, v247
	v_add_f32_e32 v240, v240, v248
	v_add_f32_e32 v241, v241, v249
	v_add_f32_e32 v242, v242, v250
	v_add_f32_e32 v243, v243, v251
	v_add_f32_e32 v244, v244, v252
	v_add_f32_e32 v245, v245, v253
	v_cvt_pk_bf16_f32 v60, v238, v239
	v_cvt_pk_bf16_f32 v61, v240, v241
	v_cvt_pk_bf16_f32 v62, v242, v243
	v_cvt_pk_bf16_f32 v63, v244, v245
	s_mov_b32 s98, 0x100000
	v_lshl_add_u64 v[234:235], v[158:159], 0, s[98:99]
	global_store_dwordx4 v[234:235], v[60:63], off
	s_waitcnt vmcnt(9)
	v_pk_add_f32 v[44:45], v[44:45], v[84:85]
	v_pk_add_f32 v[46:47], v[46:47], v[86:87]
	v_pk_add_f32 v[40:41], v[40:41], v[72:73]
	v_pk_add_f32 v[42:43], v[42:43], v[74:75]
	v_pk_add_f32 v[36:37], v[36:37], v[76:77]
	v_pk_add_f32 v[38:39], v[38:39], v[78:79]
	v_pk_add_f32 v[32:33], v[32:33], v[68:69]
	v_pk_add_f32 v[34:35], v[34:35], v[70:71]
	v_mul_f32_e32 v44, 0xbfb8aa3b, v44
	v_mul_f32_e32 v45, 0xbfb8aa3b, v45
	v_mul_f32_e32 v46, 0xbfb8aa3b, v46
	v_mul_f32_e32 v47, 0xbfb8aa3b, v47
	v_mul_f32_e32 v40, 0xbfb8aa3b, v40
	v_mul_f32_e32 v41, 0xbfb8aa3b, v41
	v_mul_f32_e32 v42, 0xbfb8aa3b, v42
	v_mul_f32_e32 v43, 0xbfb8aa3b, v43
	v_mul_f32_e32 v36, 0xbfb8aa3b, v36
	v_mul_f32_e32 v37, 0xbfb8aa3b, v37
	v_mul_f32_e32 v38, 0xbfb8aa3b, v38
	v_mul_f32_e32 v39, 0xbfb8aa3b, v39
	v_mul_f32_e32 v32, 0xbfb8aa3b, v32
	v_mul_f32_e32 v33, 0xbfb8aa3b, v33
	v_mul_f32_e32 v34, 0xbfb8aa3b, v34
	v_mul_f32_e32 v35, 0xbfb8aa3b, v35
	v_exp_f32_e32 v44, v44
	v_exp_f32_e32 v45, v45
	v_exp_f32_e32 v46, v46
	v_exp_f32_e32 v47, v47
	v_exp_f32_e32 v40, v40
	v_exp_f32_e32 v41, v41
	v_exp_f32_e32 v42, v42
	v_exp_f32_e32 v43, v43
	v_exp_f32_e32 v36, v36
	v_exp_f32_e32 v37, v37
	v_exp_f32_e32 v38, v38
	v_exp_f32_e32 v39, v39
	v_exp_f32_e32 v32, v32
	v_exp_f32_e32 v33, v33
	v_exp_f32_e32 v34, v34
	v_exp_f32_e32 v35, v35
	v_add_f32_e32 v44, 1.0, v44
	v_add_f32_e32 v45, 1.0, v45
	v_add_f32_e32 v46, 1.0, v46
	v_add_f32_e32 v47, 1.0, v47
	v_add_f32_e32 v40, 1.0, v40
	v_add_f32_e32 v41, 1.0, v41
	v_add_f32_e32 v42, 1.0, v42
	v_add_f32_e32 v43, 1.0, v43
	v_add_f32_e32 v36, 1.0, v36
	v_add_f32_e32 v37, 1.0, v37
	v_add_f32_e32 v38, 1.0, v38
	v_add_f32_e32 v39, 1.0, v39
	v_add_f32_e32 v32, 1.0, v32
	v_add_f32_e32 v33, 1.0, v33
	v_add_f32_e32 v34, 1.0, v34
	v_add_f32_e32 v35, 1.0, v35
	v_rcp_f32_e32 v44, v44
	v_rcp_f32_e32 v45, v45
	v_rcp_f32_e32 v46, v46
	v_rcp_f32_e32 v47, v47
; __device__ __forceinline__ unsigned cvt_pk_bf16(float lo, float hi) { unsigned r; asm volatile("v_cvt_pk_bf16_f32 %0, %1, %2" : "=v"(r) : "v"(lo), "v"(hi)); return r; }
; __device__ __forceinline__ float fast_sigmoid(float x) { return __builtin_amdgcn_rcpf(1.0f + __builtin_amdgcn_exp2f(-1.4426950408889634f * x)); }
;     __device__ __forceinline__ void operator()(const f32x4 (&acc)[2][2][4][2], const Unit& u, int wr, int wc, int fr, int fq) const {
;     ...
;         const f32x4 ba0 = *(const f32x4*)((const char*)bgp + boff), ba1 = *(const f32x4*)((const char*)bgp + boff + 16), bf0 = *(const f32x4*)((const char*)bgp + 16384 + boff), bf1 = *(const f32x4*)((const char*)bgp + 16384 + boff + 16);
; #pragma unroll
;         for (int ai = 0; ai < 2; ++ai)
; #pragma unroll
;             for (int m = 0; m < 4; ++m) { const size_t ro = (size_t)(ai * HALF + m * 16) * 4096 * 2;
;                 const v4u a = *(const v4u*)(yab + ro + loff), f = *(const v4u*)(yfb + ro + loff);
;                 const f32x4 ga0 = acc[ai][0][m][0] + ba0, ga1 = acc[ai][0][m][1] + ba1, gf0 = acc[ai][1][m][0] + bf0, gf1 = acc[ai][1][m][1] + bf1;
;                 float r[8];
;                 r[0] = fast_sigmoid(ga0[0]) * bflo(a.x) + fast_sigmoid(gf0[0]) * bflo(f.x); r[1] = fast_sigmoid(ga0[1]) * bfhi(a.x) + fast_sigmoid(gf0[1]) * bfhi(f.x);
;                 r[2] = fast_sigmoid(ga0[2]) * bflo(a.y) + fast_sigmoid(gf0[2]) * bflo(f.y); r[3] = fast_sigmoid(ga0[3]) * bfhi(a.y) + fast_sigmoid(gf0[3]) * bfhi(f.y);
;                 r[4] = fast_sigmoid(ga1[0]) * bflo(a.z) + fast_sigmoid(gf1[0]) * bflo(f.z); r[5] = fast_sigmoid(ga1[1]) * bfhi(a.z) + fast_sigmoid(gf1[1]) * bfhi(f.z);
;                 r[6] = fast_sigmoid(ga1[2]) * bflo(a.w) + fast_sigmoid(gf1[2]) * bflo(f.w); r[7] = fast_sigmoid(ga1[3]) * bfhi(a.w) + fast_sigmoid(gf1[3]) * bfhi(f.w);
;                 v4u w; w.x = cvt_pk_bf16(r[0], r[1]); w.y = cvt_pk_bf16(r[2], r[3]); w.z = cvt_pk_bf16(r[4], r[5]); w.w = cvt_pk_bf16(r[6], r[7]);
;                 *(v4u*)(mxb + ro + loff) = w; }
	v_rcp_f32_e32 v40, v40
	v_rcp_f32_e32 v41, v41
	v_rcp_f32_e32 v42, v42
	v_rcp_f32_e32 v43, v43
	v_rcp_f32_e32 v36, v36
	v_rcp_f32_e32 v37, v37
	v_rcp_f32_e32 v38, v38
	v_rcp_f32_e32 v39, v39
	v_rcp_f32_e32 v32, v32
	v_rcp_f32_e32 v33, v33
	v_rcp_f32_e32 v34, v34
	v_rcp_f32_e32 v35, v35
	v_lshlrev_b32_e32 v238, 16, v214
	v_and_b32_e32 v239, 0xffff0000, v214
	v_lshlrev_b32_e32 v240, 16, v215
	v_and_b32_e32 v241, 0xffff0000, v215
	v_lshlrev_b32_e32 v242, 16, v216
	v_and_b32_e32 v243, 0xffff0000, v216
	v_lshlrev_b32_e32 v244, 16, v217
	v_and_b32_e32 v245, 0xffff0000, v217
	v_lshlrev_b32_e32 v246, 16, v210
	v_and_b32_e32 v247, 0xffff0000, v210
	v_lshlrev_b32_e32 v248, 16, v211
	v_and_b32_e32 v249, 0xffff0000, v211
	v_lshlrev_b32_e32 v250, 16, v212
	v_and_b32_e32 v251, 0xffff0000, v212
	v_lshlrev_b32_e32 v252, 16, v213
	v_and_b32_e32 v253, 0xffff0000, v213
	v_mul_f32_e32 v238, v44, v238
	v_mul_f32_e32 v239, v45, v239
	v_mul_f32_e32 v240, v46, v240
	v_mul_f32_e32 v241, v47, v241
	v_mul_f32_e32 v242, v40, v242
	v_mul_f32_e32 v243, v41, v243
	v_mul_f32_e32 v244, v42, v244
	v_mul_f32_e32 v245, v43, v245
	v_mul_f32_e32 v246, v36, v246
	v_mul_f32_e32 v247, v37, v247
	v_mul_f32_e32 v248, v38, v248
	v_mul_f32_e32 v249, v39, v249
	v_mul_f32_e32 v250, v32, v250
	v_mul_f32_e32 v251, v33, v251
	v_mul_f32_e32 v252, v34, v252
	v_mul_f32_e32 v253, v35, v253
	v_add_f32_e32 v238, v238, v246
	v_add_f32_e32 v239, v239, v247
	v_add_f32_e32 v240, v240, v248
	v_add_f32_e32 v241, v241, v249
	v_add_f32_e32 v242, v242, v250
	v_add_f32_e32 v243, v243, v251
	v_add_f32_e32 v244, v244, v252
	v_add_f32_e32 v245, v245, v253
	v_cvt_pk_bf16_f32 v44, v238, v239
	v_cvt_pk_bf16_f32 v45, v240, v241
	v_cvt_pk_bf16_f32 v46, v242, v243
	v_cvt_pk_bf16_f32 v47, v244, v245
	s_mov_b32 s98, 0x120000
	v_lshl_add_u64 v[234:235], v[158:159], 0, s[98:99]
	global_store_dwordx4 v[234:235], v[44:47], off
	s_waitcnt vmcnt(8)
	v_pk_add_f32 v[28:29], v[28:29], v[84:85]
	v_pk_add_f32 v[30:31], v[30:31], v[86:87]
	v_pk_add_f32 v[24:25], v[24:25], v[72:73]
	v_pk_add_f32 v[26:27], v[26:27], v[74:75]
	v_pk_add_f32 v[20:21], v[20:21], v[76:77]
	v_pk_add_f32 v[22:23], v[22:23], v[78:79]
	v_pk_add_f32 v[16:17], v[16:17], v[68:69]
	v_pk_add_f32 v[18:19], v[18:19], v[70:71]
	v_mul_f32_e32 v28, 0xbfb8aa3b, v28
	v_mul_f32_e32 v29, 0xbfb8aa3b, v29
	v_mul_f32_e32 v30, 0xbfb8aa3b, v30
	v_mul_f32_e32 v31, 0xbfb8aa3b, v31
	v_mul_f32_e32 v24, 0xbfb8aa3b, v24
	v_mul_f32_e32 v25, 0xbfb8aa3b, v25
	v_mul_f32_e32 v26, 0xbfb8aa3b, v26
	v_mul_f32_e32 v27, 0xbfb8aa3b, v27
	v_mul_f32_e32 v20, 0xbfb8aa3b, v20
	v_mul_f32_e32 v21, 0xbfb8aa3b, v21
	v_mul_f32_e32 v22, 0xbfb8aa3b, v22
	v_mul_f32_e32 v23, 0xbfb8aa3b, v23
	v_mul_f32_e32 v16, 0xbfb8aa3b, v16
	v_mul_f32_e32 v17, 0xbfb8aa3b, v17
	v_mul_f32_e32 v18, 0xbfb8aa3b, v18
	v_mul_f32_e32 v19, 0xbfb8aa3b, v19
	v_exp_f32_e32 v28, v28
	v_exp_f32_e32 v29, v29
	v_exp_f32_e32 v30, v30
	v_exp_f32_e32 v31, v31
	v_exp_f32_e32 v24, v24
	v_exp_f32_e32 v25, v25
	v_exp_f32_e32 v26, v26
	v_exp_f32_e32 v27, v27
	v_exp_f32_e32 v20, v20
	v_exp_f32_e32 v21, v21
	v_exp_f32_e32 v22, v22
	v_exp_f32_e32 v23, v23
	v_exp_f32_e32 v16, v16
	v_exp_f32_e32 v17, v17
	v_exp_f32_e32 v18, v18
	v_exp_f32_e32 v19, v19
	v_add_f32_e32 v28, 1.0, v28
	v_add_f32_e32 v29, 1.0, v29
	v_add_f32_e32 v30, 1.0, v30
	v_add_f32_e32 v31, 1.0, v31
	v_add_f32_e32 v24, 1.0, v24
	v_add_f32_e32 v25, 1.0, v25
	v_add_f32_e32 v26, 1.0, v26
	v_add_f32_e32 v27, 1.0, v27
	v_add_f32_e32 v20, 1.0, v20
	v_add_f32_e32 v21, 1.0, v21
	v_add_f32_e32 v22, 1.0, v22
	v_add_f32_e32 v23, 1.0, v23
	v_add_f32_e32 v16, 1.0, v16
	v_add_f32_e32 v17, 1.0, v17
	v_add_f32_e32 v18, 1.0, v18
	v_add_f32_e32 v19, 1.0, v19
	v_rcp_f32_e32 v28, v28
	v_rcp_f32_e32 v29, v29
	v_rcp_f32_e32 v30, v30
	v_rcp_f32_e32 v31, v31
	v_rcp_f32_e32 v24, v24
	v_rcp_f32_e32 v25, v25
	v_rcp_f32_e32 v26, v26
	v_rcp_f32_e32 v27, v27
	v_rcp_f32_e32 v20, v20
	v_rcp_f32_e32 v21, v21
	v_rcp_f32_e32 v22, v22
	v_rcp_f32_e32 v23, v23
	v_rcp_f32_e32 v16, v16
	v_rcp_f32_e32 v17, v17
	v_rcp_f32_e32 v18, v18
	v_rcp_f32_e32 v19, v19
	v_lshlrev_b32_e32 v238, 16, v222
	v_and_b32_e32 v239, 0xffff0000, v222
	v_lshlrev_b32_e32 v240, 16, v223
	v_and_b32_e32 v241, 0xffff0000, v223
	v_lshlrev_b32_e32 v242, 16, v224
	v_and_b32_e32 v243, 0xffff0000, v224
	v_lshlrev_b32_e32 v244, 16, v225
	v_and_b32_e32 v245, 0xffff0000, v225
	v_lshlrev_b32_e32 v246, 16, v218
	v_and_b32_e32 v247, 0xffff0000, v218
	v_lshlrev_b32_e32 v248, 16, v219
	v_and_b32_e32 v249, 0xffff0000, v219
	v_lshlrev_b32_e32 v250, 16, v220
	v_and_b32_e32 v251, 0xffff0000, v220
	v_lshlrev_b32_e32 v252, 16, v221
	v_and_b32_e32 v253, 0xffff0000, v221
	v_mul_f32_e32 v238, v28, v238
	v_mul_f32_e32 v239, v29, v239
	v_mul_f32_e32 v240, v30, v240
	v_mul_f32_e32 v241, v31, v241
	v_mul_f32_e32 v242, v24, v242
	v_mul_f32_e32 v243, v25, v243
	v_mul_f32_e32 v244, v26, v244
	v_mul_f32_e32 v245, v27, v245
	v_mul_f32_e32 v246, v20, v246
	v_mul_f32_e32 v247, v21, v247
	v_mul_f32_e32 v248, v22, v248
	v_mul_f32_e32 v249, v23, v249
	v_mul_f32_e32 v250, v16, v250
	v_mul_f32_e32 v251, v17, v251
	v_mul_f32_e32 v252, v18, v252
	v_mul_f32_e32 v253, v19, v253
	v_add_f32_e32 v238, v238, v246
	v_add_f32_e32 v239, v239, v247
	v_add_f32_e32 v240, v240, v248
	v_add_f32_e32 v241, v241, v249
	v_add_f32_e32 v242, v242, v250
	v_add_f32_e32 v243, v243, v251
	v_add_f32_e32 v244, v244, v252
	v_add_f32_e32 v245, v245, v253
	v_cvt_pk_bf16_f32 v28, v238, v239
	v_cvt_pk_bf16_f32 v29, v240, v241
	v_cvt_pk_bf16_f32 v30, v242, v243
	v_cvt_pk_bf16_f32 v31, v244, v245
	s_mov_b32 s98, 0x140000
	v_lshl_add_u64 v[234:235], v[158:159], 0, s[98:99]
	global_store_dwordx4 v[234:235], v[28:31], off
	s_waitcnt vmcnt(7)
; __device__ __forceinline__ unsigned cvt_pk_bf16(float lo, float hi) { unsigned r; asm volatile("v_cvt_pk_bf16_f32 %0, %1, %2" : "=v"(r) : "v"(lo), "v"(hi)); return r; }
; __device__ __forceinline__ float fast_sigmoid(float x) { return __builtin_amdgcn_rcpf(1.0f + __builtin_amdgcn_exp2f(-1.4426950408889634f * x)); }
;     __device__ __forceinline__ void operator()(const f32x4 (&acc)[2][2][4][2], const Unit& u, int wr, int wc, int fr, int fq) const {
;     ...
;             for (int m = 0; m < 4; ++m) { const size_t ro = (size_t)(ai * HALF + m * 16) * 4096 * 2;
;                 const v4u a = *(const v4u*)(yab + ro + loff), f = *(const v4u*)(yfb + ro + loff);
;                 const f32x4 ga0 = acc[ai][0][m][0] + ba0, ga1 = acc[ai][0][m][1] + ba1, gf0 = acc[ai][1][m][0] + bf0, gf1 = acc[ai][1][m][1] + bf1;
;                 float r[8];
;                 r[0] = fast_sigmoid(ga0[0]) * bflo(a.x) + fast_sigmoid(gf0[0]) * bflo(f.x); r[1] = fast_sigmoid(ga0[1]) * bfhi(a.x) + fast_sigmoid(gf0[1]) * bfhi(f.x);
;                 r[2] = fast_sigmoid(ga0[2]) * bflo(a.y) + fast_sigmoid(gf0[2]) * bflo(f.y); r[3] = fast_sigmoid(ga0[3]) * bfhi(a.y) + fast_sigmoid(gf0[3]) * bfhi(f.y);
;                 r[4] = fast_sigmoid(ga1[0]) * bflo(a.z) + fast_sigmoid(gf1[0]) * bflo(f.z); r[5] = fast_sigmoid(ga1[1]) * bfhi(a.z) + fast_sigmoid(gf1[1]) * bfhi(f.z);
;                 r[6] = fast_sigmoid(ga1[2]) * bflo(a.w) + fast_sigmoid(gf1[2]) * bflo(f.w); r[7] = fast_sigmoid(ga1[3]) * bfhi(a.w) + fast_sigmoid(gf1[3]) * bfhi(f.w);
;                 v4u w; w.x = cvt_pk_bf16(r[0], r[1]); w.y = cvt_pk_bf16(r[2], r[3]); w.z = cvt_pk_bf16(r[4], r[5]); w.w = cvt_pk_bf16(r[6], r[7]);
;                 *(v4u*)(mxb + ro + loff) = w; }
; template <class Epi, class Addr, bool ALIGN_EPI = true, class Order = StaticOrder>
; __device__ __forceinline__ void gemm_phase(LAS unsigned char* lds, const Gemm g, const Order& S, const Epi& E, const int wid) {
;     ...
;         if (!has_next) break;
; #pragma unroll
;         for (int a = 0; a < 2; ++a)
; #pragma unroll
;             for (int b = 0; b < 2; ++b)
; #pragma unroll
;                 for (int m = 0; m < 4; ++m)
; #pragma unroll
;                     for (int n = 0; n < 2; ++n) acc[a][b][m][n] = (f32x4){0.f, 0.f, 0.f, 0.f};
;         cur = nxt; cA = nA; cB = nB; ++ui;
;         if constexpr (ALIGN_EPI) { if (wr == 1) PG8_BAR; }
;     }
	v_pk_add_f32 v[12:13], v[12:13], v[84:85]
	v_pk_add_f32 v[14:15], v[14:15], v[86:87]
	v_pk_add_f32 v[8:9], v[8:9], v[72:73]
	v_pk_add_f32 v[10:11], v[10:11], v[74:75]
	v_pk_add_f32 v[4:5], v[4:5], v[76:77]
	v_pk_add_f32 v[6:7], v[6:7], v[78:79]
	v_pk_add_f32 v[0:1], v[0:1], v[68:69]
	v_pk_add_f32 v[2:3], v[2:3], v[70:71]
	v_mul_f32_e32 v12, 0xbfb8aa3b, v12
	v_mul_f32_e32 v13, 0xbfb8aa3b, v13
	v_mul_f32_e32 v14, 0xbfb8aa3b, v14
	v_mul_f32_e32 v15, 0xbfb8aa3b, v15
	v_mul_f32_e32 v8, 0xbfb8aa3b, v8
	v_mul_f32_e32 v9, 0xbfb8aa3b, v9
	v_mul_f32_e32 v10, 0xbfb8aa3b, v10
	v_mul_f32_e32 v11, 0xbfb8aa3b, v11
	v_mul_f32_e32 v4, 0xbfb8aa3b, v4
	v_mul_f32_e32 v5, 0xbfb8aa3b, v5
	v_mul_f32_e32 v6, 0xbfb8aa3b, v6
	v_mul_f32_e32 v7, 0xbfb8aa3b, v7
	v_mul_f32_e32 v0, 0xbfb8aa3b, v0
	v_mul_f32_e32 v1, 0xbfb8aa3b, v1
	v_mul_f32_e32 v2, 0xbfb8aa3b, v2
	v_mul_f32_e32 v3, 0xbfb8aa3b, v3
	v_exp_f32_e32 v12, v12
	v_exp_f32_e32 v13, v13
	v_exp_f32_e32 v14, v14
	v_exp_f32_e32 v15, v15
	v_exp_f32_e32 v8, v8
	v_exp_f32_e32 v9, v9
	v_exp_f32_e32 v10, v10
	v_exp_f32_e32 v11, v11
	v_exp_f32_e32 v4, v4
	v_exp_f32_e32 v5, v5
	v_exp_f32_e32 v6, v6
	v_exp_f32_e32 v7, v7
	v_exp_f32_e32 v0, v0
	v_exp_f32_e32 v1, v1
	v_exp_f32_e32 v2, v2
	v_exp_f32_e32 v3, v3
	v_add_f32_e32 v12, 1.0, v12
	v_add_f32_e32 v13, 1.0, v13
	v_add_f32_e32 v14, 1.0, v14
	v_add_f32_e32 v15, 1.0, v15
	v_add_f32_e32 v8, 1.0, v8
	v_add_f32_e32 v9, 1.0, v9
	v_add_f32_e32 v10, 1.0, v10
	v_add_f32_e32 v11, 1.0, v11
	v_add_f32_e32 v4, 1.0, v4
	v_add_f32_e32 v5, 1.0, v5
	v_add_f32_e32 v6, 1.0, v6
	v_add_f32_e32 v7, 1.0, v7
	v_add_f32_e32 v0, 1.0, v0
	v_add_f32_e32 v1, 1.0, v1
	v_add_f32_e32 v2, 1.0, v2
	v_add_f32_e32 v3, 1.0, v3
	v_rcp_f32_e32 v12, v12
	v_rcp_f32_e32 v13, v13
	v_rcp_f32_e32 v14, v14
	v_rcp_f32_e32 v15, v15
	v_rcp_f32_e32 v8, v8
	v_rcp_f32_e32 v9, v9
	v_rcp_f32_e32 v10, v10
	v_rcp_f32_e32 v11, v11
	v_rcp_f32_e32 v4, v4
	v_rcp_f32_e32 v5, v5
	v_rcp_f32_e32 v6, v6
	v_rcp_f32_e32 v7, v7
	v_rcp_f32_e32 v0, v0
	v_rcp_f32_e32 v1, v1
	v_rcp_f32_e32 v2, v2
	v_rcp_f32_e32 v3, v3
	v_lshlrev_b32_e32 v238, 16, v230
	v_and_b32_e32 v239, 0xffff0000, v230
	v_lshlrev_b32_e32 v240, 16, v231
	v_and_b32_e32 v241, 0xffff0000, v231
	v_lshlrev_b32_e32 v242, 16, v232
	v_and_b32_e32 v243, 0xffff0000, v232
	v_lshlrev_b32_e32 v244, 16, v233
	v_and_b32_e32 v245, 0xffff0000, v233
	v_lshlrev_b32_e32 v246, 16, v226
	v_and_b32_e32 v247, 0xffff0000, v226
	v_lshlrev_b32_e32 v248, 16, v227
	v_and_b32_e32 v249, 0xffff0000, v227
	v_lshlrev_b32_e32 v250, 16, v228
	v_and_b32_e32 v251, 0xffff0000, v228
	v_lshlrev_b32_e32 v252, 16, v229
	v_and_b32_e32 v253, 0xffff0000, v229
	v_mul_f32_e32 v238, v12, v238
	v_mul_f32_e32 v239, v13, v239
	v_mul_f32_e32 v240, v14, v240
	v_mul_f32_e32 v241, v15, v241
	v_mul_f32_e32 v242, v8, v242
	v_mul_f32_e32 v243, v9, v243
	v_mul_f32_e32 v244, v10, v244
	v_mul_f32_e32 v245, v11, v245
	v_mul_f32_e32 v246, v4, v246
	v_mul_f32_e32 v247, v5, v247
	v_mul_f32_e32 v248, v6, v248
	v_mul_f32_e32 v249, v7, v249
	v_mul_f32_e32 v250, v0, v250
	v_mul_f32_e32 v251, v1, v251
	v_mul_f32_e32 v252, v2, v252
	v_mul_f32_e32 v253, v3, v253
	v_add_f32_e32 v238, v238, v246
	v_add_f32_e32 v239, v239, v247
	v_add_f32_e32 v240, v240, v248
	v_add_f32_e32 v241, v241, v249
	v_add_f32_e32 v242, v242, v250
	v_add_f32_e32 v243, v243, v251
	v_add_f32_e32 v244, v244, v252
	v_add_f32_e32 v245, v245, v253
	v_cvt_pk_bf16_f32 v12, v238, v239
	v_cvt_pk_bf16_f32 v13, v240, v241
	v_cvt_pk_bf16_f32 v14, v242, v243
	v_cvt_pk_bf16_f32 v15, v244, v245
	s_mov_b32 s98, 0x160000
	v_lshl_add_u64 v[234:235], v[158:159], 0, s[98:99]
	s_andn2_b64 vcc, exec, s[4:5]
	s_mov_b64 s[4:5], -1
	global_store_dwordx4 v[234:235], v[12:15], off
	s_cbranch_vccnz .LBB0_725
	s_andn2_b64 vcc, exec, s[8:9]
	s_cbranch_vccnz .LBB0_724
	s_barrier
	s_branch .LBB0_724

; __global__ void __launch_bounds__(NWAVES * 64, 2) fwd(Args args) {
	.amdhsa_kernel _Z3fwd4Args
		.amdhsa_group_segment_fixed_size 0
		.amdhsa_private_segment_fixed_size 0
		.amdhsa_kernarg_size 456
		.amdhsa_user_sgpr_count 2
		.amdhsa_user_sgpr_dispatch_ptr 0
		.amdhsa_user_sgpr_queue_ptr 0
		.amdhsa_user_sgpr_kernarg_segment_ptr 1
		.amdhsa_user_sgpr_dispatch_id 0
		.amdhsa_user_sgpr_kernarg_preload_length 0
		.amdhsa_user_sgpr_kernarg_preload_offset 0
		.amdhsa_user_sgpr_private_segment_size 0
		.amdhsa_uses_dynamic_stack 0
		.amdhsa_enable_private_segment 0
		.amdhsa_system_sgpr_workgroup_id_x 1
		.amdhsa_system_sgpr_workgroup_id_y 0
		.amdhsa_system_sgpr_workgroup_id_z 0
		.amdhsa_system_sgpr_workgroup_info 0
		.amdhsa_system_vgpr_workitem_id 0
		.amdhsa_next_free_vgpr 255
		.amdhsa_next_free_sgpr 102
		.amdhsa_accum_offset 256
		.amdhsa_reserve_vcc 1
		.amdhsa_float_round_mode_32 0
		.amdhsa_float_round_mode_16_64 0
		.amdhsa_float_denorm_mode_32 3
		.amdhsa_float_denorm_mode_16_64 3
		.amdhsa_dx10_clamp 1
		.amdhsa_ieee_mode 1
		.amdhsa_fp16_overflow 0
		.amdhsa_tg_split 0
		.amdhsa_exception_fp_ieee_invalid_op 0
		.amdhsa_exception_fp_denorm_src 0
		.amdhsa_exception_fp_ieee_div_zero 0
		.amdhsa_exception_fp_ieee_overflow 0
		.amdhsa_exception_fp_ieee_underflow 0
		.amdhsa_exception_fp_ieee_inexact 0
		.amdhsa_exception_int_div_zero 0
	.end_amdhsa_kernel

; __global__ void __launch_bounds__(NWAVES * 64, 2) fwd(Args args) {
amdhsa.kernels:
  - .agpr_count:     0
    .args:
      - .offset:         0
        .size:           200
        .value_kind:     by_value
      - .offset:         200
        .size:           4
        .value_kind:     hidden_block_count_x
      - .offset:         204
        .size:           4
        .value_kind:     hidden_block_count_y
      - .offset:         208
        .size:           4
        .value_kind:     hidden_block_count_z
      - .offset:         212
        .size:           2
        .value_kind:     hidden_group_size_x
      - .offset:         214
        .size:           2
        .value_kind:     hidden_group_size_y
      - .offset:         216
        .size:           2
        .value_kind:     hidden_group_size_z
      - .offset:         218
        .size:           2
        .value_kind:     hidden_remainder_x
      - .offset:         220
        .size:           2
        .value_kind:     hidden_remainder_y
      - .offset:         222
        .size:           2
        .value_kind:     hidden_remainder_z
      - .offset:         240
        .size:           8
        .value_kind:     hidden_global_offset_x
      - .offset:         248
        .size:           8
        .value_kind:     hidden_global_offset_y
      - .offset:         256
        .size:           8
        .value_kind:     hidden_global_offset_z
      - .offset:         264
        .size:           2
        .value_kind:     hidden_grid_dims
      - .offset:         320
        .size:           4
        .value_kind:     hidden_dynamic_lds_size
    .group_segment_fixed_size: 0
    .kernarg_segment_align: 8
    .kernarg_segment_size: 456
    .language:       OpenCL C
    .language_version:
      - 2
      - 0
    .max_flat_workgroup_size: 512
    .name:           _Z3fwd4Args
    .private_segment_fixed_size: 0
    .sgpr_count:     108
    .sgpr_spill_count: 9
    .symbol:         _Z3fwd4Args.kd
    .uniform_work_group_size: 1
    .uses_dynamic_stack: false
    .vgpr_count:     255
    .vgpr_spill_count: 0
    .wavefront_size: 64
